# P1 K-loop: barrier moved between the two MFMA bursts of a K-step, next-step fragments prefetched into second register set, DMA prefetch distance 4
# speedup vs baseline: 1.0393x; 1.0097x over previous
.LBB0_376:
	s_or_b64 exec, exec, s[6:7]
	s_add_u32 s0, s64, 0x940000
	s_addc_u32 s1, s65, 0
	v_writelane_b32 v254, s0, 2
	s_add_u32 s94, s64, 0x4940000
	s_addc_u32 s95, s65, 0
	v_writelane_b32 v254, s1, 3
	v_lshrrev_b32_e32 v135, 5, v130
	v_readlane_b32 s0, v254, 4
	v_readlane_b32 s1, v254, 5
	s_and_b32 s79, s0, 7
	s_ashr_i32 s2, s0, 3
	v_readlane_b32 s0, v254, 6
	s_ashr_i32 s74, s0, 3
	s_lshl_b32 s85, s79, 4
	s_add_u32 s52, s64, 0xf140000
	s_addc_u32 s53, s65, 0
	v_readlane_b32 s1, v254, 7
	s_add_u32 s0, s64, 0xb140000
	s_addc_u32 s1, s65, 0
	v_writelane_b32 v254, s0, 8
	v_lshrrev_b32_e32 v2, 2, v128
	v_bfe_u32 v3, v128, 2, 2
	v_writelane_b32 v254, s1, 9
	s_add_u32 s0, s64, 0x9140000
	s_addc_u32 s1, s65, 0
	v_bitop3_b32 v2, v135, v2, 3 bitop3:0x78
	v_writelane_b32 v254, s0, 10
	v_lshrrev_b32_e32 v0, 4, v128
	v_lshlrev_b32_e32 v188, 4, v2
	v_bitop3_b32 v2, v135, v3, 2 bitop3:0x36
	v_writelane_b32 v254, s1, 11
	s_add_u32 s0, s64, 0x10340000
	v_xor_b32_e32 v0, v0, v128
	v_lshlrev_b32_e32 v190, 4, v2
	v_mov_b32_e32 v2, 0x11c40000
	v_mov_b32_e32 v3, 0x10140000
	s_addc_u32 s1, s65, 0
	v_and_b32_e32 v208, 30, v1
	v_lshlrev_b32_e32 v1, 3, v0
	v_cndmask_b32_e64 v140, v2, v3, s[4:5]
	v_lshlrev_b32_e32 v2, 11, v132
	v_writelane_b32 v254, s0, 12
	v_and_b32_e32 v1, 24, v1
	v_mov_b32_e32 v141, 0
	v_lshl_or_b32 v201, v135, 3, v2
	v_writelane_b32 v254, s1, 13
	s_cmpk_gt_i32 s2, 0xbf
	v_lshrrev_b32_e32 v129, 2, v130
	v_lshlrev_b32_e32 v207, 7, v135
	v_lshlrev_b32_e32 v189, 6, v132
	v_or_b32_e32 v194, 2, v135
	v_lshlrev_b32_e32 v134, 2, v135
	v_or_b32_e32 v206, 32, v132
	v_lshl_add_u64 v[138:139], s[64:65], 0, v[140:141]
	v_lshlrev_b32_e32 v205, 12, v135
	v_or_b32_e32 v204, 0x10000, v201
	v_lshlrev_b32_e32 v203, 11, v135
	v_cmp_gt_u32_e64 s[6:7], 8, v132
	v_lshlrev_b32_e32 v136, 1, v1
	s_barrier
	v_writelane_b32 v254, s2, 14
	s_cbranch_scc1 .LBB0_477
	v_readlane_b32 s0, v254, 2
	v_and_b32_e32 v0, 3, v0
	v_mov_b32_e32 v137, v141
	v_readlane_b32 s1, v254, 3
	v_lshlrev_b32_e32 v140, 4, v0
	v_or_b32_e32 v192, 0xfffff800, v202
	v_or_b32_e32 v193, 16, v132
	v_lshl_add_u64 v[142:143], s[0:1], 0, v[136:137]
	v_lshl_add_u64 v[144:145], s[64:65], 0, v[136:137]
	v_lshl_add_u64 v[146:147], s[64:65], 0, v[140:141]
	v_or_b32_e32 v137, 16, v129
	s_mov_b64 s[12:13], 0x80
	s_add_i32 s28, 0, 0x10000
	s_add_i32 s29, 0, 0x14000
	s_mov_b64 s[14:15], 0x9400c0
	s_mov_b64 s[16:17], 0xc0
	s_mov_b64 s[18:19], 0x940100
	s_mov_b64 s[20:21], 0x100
	s_mov_b64 s[60:61], 0x940140
	s_mov_b64 s[62:63], 0x140
	s_mov_b32 s30, 0x10440000
	s_movk_i32 s31, 0xf680
	s_movk_i32 s33, 0xfa00
	s_mov_b32 s34, 0x5140000
	v_readlane_b32 s35, v254, 14
	s_branch .LBB0_379

.LBB0_381:
	s_lshr_b32 s2, s2, 6
	s_lshl_b32 s27, s2, 5
	v_or_b32_e32 v2, s27, v129
	v_add_u32_e32 v0, s3, v2
	s_or_b32 s40, s27, 16
	v_ashrrev_i32_e32 v1, 31, v0
	s_lshl_b32 s2, s2, 11
	v_add_u32_e32 v2, s24, v2
	v_or_b32_e32 v6, s40, v129
	v_lshlrev_b64 v[0:1], 11, v[0:1]
	s_add_i32 s39, s2, 0
	v_ashrrev_i32_e32 v3, 31, v2
	v_add_u32_e32 v4, s3, v6
	v_lshl_add_u64 v[0:1], v[142:143], 0, v[0:1]
	s_mov_b32 m0, s39
	v_lshlrev_b64 v[2:3], 11, v[2:3]
	v_ashrrev_i32_e32 v5, 31, v4
	s_lshl_b32 s3, s40, 6
	v_add_u32_e32 v6, s24, v6
	s_waitcnt lgkmcnt(0)
	s_barrier
	global_load_lds_dwordx4 v[0:1], off
	v_lshl_add_u64 v[2:3], v[144:145], 0, v[2:3]
	s_add_i32 m0, s39, 0x4000
	v_lshlrev_b64 v[4:5], 11, v[4:5]
	s_add_i32 s40, s3, 0
	v_ashrrev_i32_e32 v7, 31, v6
	global_load_lds_dwordx4 v[2:3], off
	v_lshl_add_u64 v[4:5], v[142:143], 0, v[4:5]
	s_mov_b32 m0, s40
	v_lshlrev_b64 v[6:7], 11, v[6:7]
	global_load_lds_dwordx4 v[4:5], off
	v_lshl_add_u64 v[6:7], v[144:145], 0, v[6:7]
	s_add_i32 m0, s40, 0x4000
	v_lshl_add_u64 v[8:9], v[0:1], 0, 64
	global_load_lds_dwordx4 v[6:7], off
	s_add_i32 m0, s39, 0x8000
	v_lshl_add_u64 v[0:1], v[0:1], 0, s[12:13]
	global_load_lds_dwordx4 v[8:9], off
	v_lshl_add_u64 v[8:9], v[2:3], 0, 64
	s_add_i32 m0, s39, 0xc000
	s_add_i32 s24, s27, s24
	global_load_lds_dwordx4 v[8:9], off
	v_lshl_add_u64 v[8:9], v[4:5], 0, 64
	s_add_i32 m0, s40, 0x8000
	s_add_i32 s23, s23, s22
	global_load_lds_dwordx4 v[8:9], off
	v_lshl_add_u64 v[8:9], v[6:7], 0, 64
	s_add_i32 m0, s40, 0xc000
	s_lshl_b32 s22, s23, 8
	global_load_lds_dwordx4 v[8:9], off
	s_add_i32 m0, s28, s2
	s_add_i32 s27, s27, s22
	global_load_lds_dwordx4 v[0:1], off
	v_lshl_add_u64 v[0:1], v[2:3], 0, s[12:13]
	s_add_i32 m0, s29, s2
	v_lshl_or_b32 v195, s25, 13, v189
	global_load_lds_dwordx4 v[0:1], off
	v_lshl_add_u64 v[0:1], v[4:5], 0, s[12:13]
	s_add_i32 m0, s28, s3
	s_mov_b64 s[22:23], 0
	global_load_lds_dwordx4 v[0:1], off
	v_lshl_add_u64 v[0:1], v[6:7], 0, s[12:13]
	s_add_i32 m0, s29, s3
	s_mov_b32 s39, 1
	global_load_lds_dwordx4 v[0:1], off
	v_or_b32_e32 v0, s26, v132
	v_lshlrev_b32_e32 v140, 6, v0
	v_add_u32_e32 v0, s24, v137
	v_ashrrev_i32_e32 v1, 31, v0
	v_lshlrev_b64 v[0:1], 11, v[0:1]
	v_lshl_add_u64 v[180:181], v[146:147], 0, v[0:1]
	v_or_b32_e32 v0, s27, v137
	v_ashrrev_i32_e32 v1, 31, v0
	v_lshlrev_b64 v[0:1], 11, v[0:1]
	v_lshl_add_u64 v[182:183], v[146:147], 0, v[0:1]
	v_add_u32_e32 v0, s24, v129
	v_ashrrev_i32_e32 v1, 31, v0
	v_lshlrev_b64 v[0:1], 11, v[0:1]
	v_lshl_add_u64 v[184:185], v[146:147], 0, v[0:1]
	v_or_b32_e32 v0, s27, v129
	v_ashrrev_i32_e32 v1, 31, v0
	v_lshlrev_b64 v[0:1], 11, v[0:1]
	v_lshl_add_u64 v[186:187], v[146:147], 0, v[0:1]
	s_mov_b32 s51, 0x18000
	s_add_i32 s55, s51, s2
	s_add_i32 s54, s51, s3
	s_mov_b32 m0, s55
	v_lshl_add_u64 v[196:197], v[186:187], 0, s[14:15]
	global_load_lds_dwordx4 v[196:197], off
	s_add_i32 m0, s55, 0x4000
	v_lshl_add_u64 v[196:197], v[184:185], 0, s[16:17]
	global_load_lds_dwordx4 v[196:197], off
	s_mov_b32 m0, s54
	v_lshl_add_u64 v[196:197], v[182:183], 0, s[14:15]
	global_load_lds_dwordx4 v[196:197], off
	s_add_i32 m0, s54, 0x4000
	v_lshl_add_u64 v[196:197], v[180:181], 0, s[16:17]
	global_load_lds_dwordx4 v[196:197], off
	v_mov_b32_e32 v0, 0
	s_mov_b32 s40, 0
	v_mov_b32_e32 v1, v0
	v_mov_b32_e32 v2, v0
	v_mov_b32_e32 v3, v0
	v_mov_b32_e32 v4, v0
	v_mov_b32_e32 v5, v0
	v_mov_b32_e32 v6, v0
	v_mov_b32_e32 v7, v0
	v_mov_b32_e32 v8, v0
	v_mov_b32_e32 v9, v0
	v_mov_b32_e32 v10, v0
	v_mov_b32_e32 v11, v0
	v_mov_b32_e32 v12, v0
	v_mov_b32_e32 v13, v0
	v_mov_b32_e32 v14, v0
	v_mov_b32_e32 v15, v0
	v_mov_b32_e32 v16, v0
	v_mov_b32_e32 v17, v0
	v_mov_b32_e32 v18, v0
	v_mov_b32_e32 v19, v0
	v_mov_b32_e32 v20, v0
	v_mov_b32_e32 v21, v0
	v_mov_b32_e32 v22, v0
	v_mov_b32_e32 v23, v0
	v_mov_b32_e32 v24, v0
	v_mov_b32_e32 v25, v0
	v_mov_b32_e32 v26, v0
	v_mov_b32_e32 v27, v0
	v_mov_b32_e32 v28, v0
	v_mov_b32_e32 v29, v0
	v_mov_b32_e32 v30, v0
	v_mov_b32_e32 v31, v0
	v_mov_b32_e32 v32, v0
	v_mov_b32_e32 v33, v0
	v_mov_b32_e32 v34, v0
	v_mov_b32_e32 v35, v0
	v_mov_b32_e32 v36, v0
	v_mov_b32_e32 v37, v0
	v_mov_b32_e32 v38, v0
	v_mov_b32_e32 v39, v0
	v_mov_b32_e32 v40, v0
	v_mov_b32_e32 v41, v0
	v_mov_b32_e32 v42, v0
	v_mov_b32_e32 v43, v0
	v_mov_b32_e32 v44, v0
	v_mov_b32_e32 v45, v0
	v_mov_b32_e32 v46, v0
	v_mov_b32_e32 v47, v0
	v_mov_b32_e32 v48, v0
	v_mov_b32_e32 v49, v0
	v_mov_b32_e32 v50, v0
	v_mov_b32_e32 v51, v0
	v_mov_b32_e32 v52, v0
	v_mov_b32_e32 v53, v0
	v_mov_b32_e32 v54, v0
	v_mov_b32_e32 v55, v0
	v_mov_b32_e32 v56, v0
	v_mov_b32_e32 v57, v0
	v_mov_b32_e32 v58, v0
	v_mov_b32_e32 v59, v0
	v_mov_b32_e32 v60, v0
	v_mov_b32_e32 v61, v0
	v_mov_b32_e32 v62, v0
	v_mov_b32_e32 v63, v0
	v_mov_b32_e32 v64, v0
	v_mov_b32_e32 v65, v0
	v_mov_b32_e32 v66, v0
	v_mov_b32_e32 v67, v0
	v_mov_b32_e32 v68, v0
	v_mov_b32_e32 v69, v0
	v_mov_b32_e32 v70, v0
	v_mov_b32_e32 v71, v0
	v_mov_b32_e32 v72, v0
	v_mov_b32_e32 v73, v0
	v_mov_b32_e32 v74, v0
	v_mov_b32_e32 v75, v0
	v_mov_b32_e32 v76, v0
	v_mov_b32_e32 v77, v0
	v_mov_b32_e32 v78, v0
	v_mov_b32_e32 v79, v0
	v_mov_b32_e32 v80, v0
	v_mov_b32_e32 v81, v0
	v_mov_b32_e32 v82, v0
	v_mov_b32_e32 v83, v0
	v_mov_b32_e32 v84, v0
	v_mov_b32_e32 v85, v0
	v_mov_b32_e32 v86, v0
	v_mov_b32_e32 v87, v0
	v_mov_b32_e32 v88, v0
	v_mov_b32_e32 v89, v0
	v_mov_b32_e32 v90, v0
	v_mov_b32_e32 v91, v0
	v_mov_b32_e32 v92, v0
	v_mov_b32_e32 v93, v0
	v_mov_b32_e32 v94, v0
	v_mov_b32_e32 v95, v0
	s_waitcnt vmcnt(12)
	v_mov_b32_e32 v96, v0
	v_mov_b32_e32 v97, v0
	v_mov_b32_e32 v98, v0
	v_mov_b32_e32 v99, v0
	v_mov_b32_e32 v100, v0
	v_mov_b32_e32 v101, v0
	v_mov_b32_e32 v102, v0
	v_mov_b32_e32 v103, v0
	v_mov_b32_e32 v104, v0
	v_mov_b32_e32 v105, v0
	v_mov_b32_e32 v106, v0
	v_mov_b32_e32 v107, v0
	v_mov_b32_e32 v108, v0
	v_mov_b32_e32 v109, v0
	v_mov_b32_e32 v110, v0
	v_mov_b32_e32 v111, v0
	v_mov_b32_e32 v112, v0
	v_mov_b32_e32 v113, v0
	v_mov_b32_e32 v114, v0
	v_mov_b32_e32 v115, v0
	v_mov_b32_e32 v116, v0
	v_mov_b32_e32 v117, v0
	v_mov_b32_e32 v118, v0
	v_mov_b32_e32 v119, v0
	v_mov_b32_e32 v120, v0
	v_mov_b32_e32 v121, v0
	v_mov_b32_e32 v122, v0
	v_mov_b32_e32 v123, v0
	v_mov_b32_e32 v124, v0
	v_mov_b32_e32 v125, v0
	v_mov_b32_e32 v126, v0
	v_mov_b32_e32 v127, v0
	s_barrier
	v_add_u32_e32 v214, v188, v140
	v_add_u32_e32 v209, v188, v195
	ds_read_b128 v[196:199], v214
	ds_read_b128 v[210:213], v209 offset:16384
	ds_read_b128 v[218:221], v209 offset:18432
	ds_read_b128 v[222:225], v209 offset:20480
	ds_read_b128 v[226:229], v209 offset:22528
	ds_read_b128 v[214:217], v214 offset:2048
	v_add_u32_e32 v238, v190, v140
	v_add_u32_e32 v250, v190, v195
	ds_read_b128 v[230:233], v238
	ds_read_b128 v[234:237], v250 offset:16384
	ds_read_b128 v[242:245], v250 offset:18432
	ds_read_b128 v[246:249], v250 offset:20480
	ds_read_b128 v[238:241], v238 offset:2048
	ds_read_b128 v[250:253], v250 offset:22528
.Lq1_even:
	s_waitcnt lgkmcnt(6)
	v_mfma_f32_32x32x16_bf16 v[48:63], v[214:217], v[210:213], v[48:63]
	v_mfma_f32_32x32x16_bf16 v[32:47], v[214:217], v[218:221], v[32:47]
	v_mfma_f32_32x32x16_bf16 v[16:31], v[214:217], v[222:225], v[16:31]
	v_mfma_f32_32x32x16_bf16 v[0:15], v[214:217], v[226:229], v[0:15]
	v_mfma_f32_32x32x16_bf16 v[112:127], v[196:199], v[210:213], v[112:127]
	v_mfma_f32_32x32x16_bf16 v[96:111], v[196:199], v[218:221], v[96:111]
	v_mfma_f32_32x32x16_bf16 v[80:95], v[196:199], v[222:225], v[80:95]
	v_mfma_f32_32x32x16_bf16 v[64:79], v[196:199], v[226:229], v[64:79]
	s_cmp_gt_u32 s39, 29
	s_cbranch_scc1 .Lq1_e_w0
	s_waitcnt vmcnt(8)
	s_branch .Lq1_e_wd

.Lq1_e_wd:
	s_waitcnt lgkmcnt(0)
	s_barrier
	s_cmp_gt_u32 s39, 28
	s_cbranch_scc1 .Lq1_e_nd
	s_and_b32 s51, s40, 0x10000
	s_add_i32 s55, s51, s2
	s_add_i32 s54, s51, s3
	v_lshl_add_u64 v[196:197], v[186:187], 0, s[22:23]
	s_mov_b32 m0, s55
	v_lshl_add_u64 v[196:197], v[196:197], 0, s[18:19]
	global_load_lds_dwordx4 v[196:197], off
	v_lshl_add_u64 v[196:197], v[184:185], 0, s[22:23]
	s_add_i32 m0, s55, 0x4000
	v_lshl_add_u64 v[196:197], v[196:197], 0, s[20:21]
	global_load_lds_dwordx4 v[196:197], off
	v_lshl_add_u64 v[196:197], v[182:183], 0, s[22:23]
	s_mov_b32 m0, s54
	v_lshl_add_u64 v[196:197], v[196:197], 0, s[18:19]
	global_load_lds_dwordx4 v[196:197], off
	v_lshl_add_u64 v[196:197], v[180:181], 0, s[22:23]
	s_add_i32 m0, s54, 0x4000
	v_lshl_add_u64 v[196:197], v[196:197], 0, s[20:21]
	global_load_lds_dwordx4 v[196:197], off
.Lq1_e_nd:
	s_add_i32 s50, s40, 0x8000
	s_and_b32 s50, s50, 0x18000
	v_add_u32_e32 v209, s50, v188
	v_add_u32_e32 v214, v209, v140
	v_add_u32_e32 v209, v209, v195
	ds_read_b128 v[196:199], v214
	ds_read_b128 v[210:213], v209 offset:16384
	ds_read_b128 v[218:221], v209 offset:18432
	ds_read_b128 v[222:225], v209 offset:20480
	ds_read_b128 v[226:229], v209 offset:22528
	ds_read_b128 v[214:217], v214 offset:2048
	v_mfma_f32_32x32x16_bf16 v[48:63], v[238:241], v[234:237], v[48:63]
	v_mfma_f32_32x32x16_bf16 v[32:47], v[238:241], v[242:245], v[32:47]
	v_mfma_f32_32x32x16_bf16 v[16:31], v[238:241], v[246:249], v[16:31]
	v_mfma_f32_32x32x16_bf16 v[0:15], v[238:241], v[250:253], v[0:15]
	v_mfma_f32_32x32x16_bf16 v[112:127], v[230:233], v[234:237], v[112:127]
	v_mfma_f32_32x32x16_bf16 v[96:111], v[230:233], v[242:245], v[96:111]
	v_mfma_f32_32x32x16_bf16 v[80:95], v[230:233], v[246:249], v[80:95]
	v_mfma_f32_32x32x16_bf16 v[64:79], v[230:233], v[250:253], v[64:79]
	v_add_u32_e32 v250, s50, v190
	v_add_u32_e32 v238, v250, v140
	v_add_u32_e32 v250, v250, v195
	ds_read_b128 v[230:233], v238
	ds_read_b128 v[234:237], v250 offset:16384
	ds_read_b128 v[242:245], v250 offset:18432
	ds_read_b128 v[246:249], v250 offset:20480
	ds_read_b128 v[238:241], v238 offset:2048
	ds_read_b128 v[250:253], v250 offset:22528
	s_waitcnt lgkmcnt(6)
	v_mfma_f32_32x32x16_bf16 v[48:63], v[214:217], v[210:213], v[48:63]
	v_mfma_f32_32x32x16_bf16 v[32:47], v[214:217], v[218:221], v[32:47]
	v_mfma_f32_32x32x16_bf16 v[16:31], v[214:217], v[222:225], v[16:31]
	v_mfma_f32_32x32x16_bf16 v[0:15], v[214:217], v[226:229], v[0:15]
	v_mfma_f32_32x32x16_bf16 v[112:127], v[196:199], v[210:213], v[112:127]
	v_mfma_f32_32x32x16_bf16 v[96:111], v[196:199], v[218:221], v[96:111]
	v_mfma_f32_32x32x16_bf16 v[80:95], v[196:199], v[222:225], v[80:95]
	v_mfma_f32_32x32x16_bf16 v[64:79], v[196:199], v[226:229], v[64:79]
	s_cmp_eq_u32 s39, 31
	s_cbranch_scc1 .Lq1_last
	s_cmp_gt_u32 s39, 28
	s_cbranch_scc1 .Lq1_o_w4
	s_waitcnt vmcnt(8)
	s_branch .Lq1_o_wd
.Lq1_o_w4:
	s_waitcnt vmcnt(4)
.Lq1_o_wd:
	s_waitcnt lgkmcnt(0)
	s_barrier
	s_cmp_gt_u32 s39, 27
	s_cbranch_scc1 .Lq1_o_nd
	s_add_i32 s51, s40, 0x8000
	s_and_b32 s51, s51, 0x18000
	s_add_i32 s55, s51, s2
	s_add_i32 s54, s51, s3
	v_lshl_add_u64 v[196:197], v[186:187], 0, s[22:23]
	s_mov_b32 m0, s55
	v_lshl_add_u64 v[196:197], v[196:197], 0, s[60:61]
	global_load_lds_dwordx4 v[196:197], off
	v_lshl_add_u64 v[196:197], v[184:185], 0, s[22:23]
	s_add_i32 m0, s55, 0x4000
	v_lshl_add_u64 v[196:197], v[196:197], 0, s[62:63]
	global_load_lds_dwordx4 v[196:197], off
	v_lshl_add_u64 v[196:197], v[182:183], 0, s[22:23]
	s_mov_b32 m0, s54
	v_lshl_add_u64 v[196:197], v[196:197], 0, s[60:61]
	global_load_lds_dwordx4 v[196:197], off
	v_lshl_add_u64 v[196:197], v[180:181], 0, s[22:23]
	s_add_i32 m0, s54, 0x4000
	v_lshl_add_u64 v[196:197], v[196:197], 0, s[62:63]
	global_load_lds_dwordx4 v[196:197], off
.Lq1_o_nd:
	s_add_i32 s50, s40, 0x10000
	s_and_b32 s50, s50, 0x10000
	v_add_u32_e32 v209, s50, v188
	v_add_u32_e32 v214, v209, v140
	v_add_u32_e32 v209, v209, v195
	ds_read_b128 v[196:199], v214
	ds_read_b128 v[210:213], v209 offset:16384
	ds_read_b128 v[218:221], v209 offset:18432
	ds_read_b128 v[222:225], v209 offset:20480
	ds_read_b128 v[226:229], v209 offset:22528
	ds_read_b128 v[214:217], v214 offset:2048
	v_mfma_f32_32x32x16_bf16 v[48:63], v[238:241], v[234:237], v[48:63]
	v_mfma_f32_32x32x16_bf16 v[32:47], v[238:241], v[242:245], v[32:47]
	v_mfma_f32_32x32x16_bf16 v[16:31], v[238:241], v[246:249], v[16:31]
	v_mfma_f32_32x32x16_bf16 v[0:15], v[238:241], v[250:253], v[0:15]
	v_mfma_f32_32x32x16_bf16 v[112:127], v[230:233], v[234:237], v[112:127]
	v_mfma_f32_32x32x16_bf16 v[96:111], v[230:233], v[242:245], v[96:111]
	v_mfma_f32_32x32x16_bf16 v[80:95], v[230:233], v[246:249], v[80:95]
	v_mfma_f32_32x32x16_bf16 v[64:79], v[230:233], v[250:253], v[64:79]
	v_add_u32_e32 v250, s50, v190
	v_add_u32_e32 v238, v250, v140
	v_add_u32_e32 v250, v250, v195
	ds_read_b128 v[230:233], v238
	ds_read_b128 v[234:237], v250 offset:16384
	ds_read_b128 v[242:245], v250 offset:18432
	ds_read_b128 v[246:249], v250 offset:20480
	ds_read_b128 v[238:241], v238 offset:2048
	ds_read_b128 v[250:253], v250 offset:22528
	s_add_u32 s22, s22, 0x80
	s_addc_u32 s23, s23, 0
	s_add_i32 s39, s39, 2
	s_add_i32 s40, s40, 0x10000
	s_branch .Lq1_even
.Lq1_last:
	s_waitcnt lgkmcnt(0)
	v_mfma_f32_32x32x16_bf16 v[48:63], v[238:241], v[234:237], v[48:63]
	v_mfma_f32_32x32x16_bf16 v[32:47], v[238:241], v[242:245], v[32:47]
	v_mfma_f32_32x32x16_bf16 v[16:31], v[238:241], v[246:249], v[16:31]
	v_mfma_f32_32x32x16_bf16 v[0:15], v[238:241], v[250:253], v[0:15]
	v_mfma_f32_32x32x16_bf16 v[112:127], v[230:233], v[234:237], v[112:127]
	v_mfma_f32_32x32x16_bf16 v[96:111], v[230:233], v[242:245], v[96:111]
	v_mfma_f32_32x32x16_bf16 v[80:95], v[230:233], v[246:249], v[80:95]
	v_mfma_f32_32x32x16_bf16 v[64:79], v[230:233], v[250:253], v[64:79]
